# K-rotation (pair offsets k0=((rank&7)+(rank>>3))&3) also in the MLP-down GEMM (K=4096); on top of dummy-prefetch skips
# baseline (speedup 1.0000x reference)
; #define PG8_BAR __builtin_amdgcn_s_barrier()
;     DI void init_issue(u32x4 (&w)[R8::HAS_PRE ? 16 : 1], const Unit& u, int wr, int wc, int fr, int fq) const {
;     ...
;             const int row0 = u.pm * BM + wr * 64 + fr, col0 = u.pn * BM + (PERM ? wc * 64 : wc * 32) + 8 * fq;
; #pragma unroll
;             for (int ai = 0; ai < 2; ++ai)
; #pragma unroll
;                 for (int m = 0; m < 4; ++m)
; #pragma unroll
; template <class Epi, class Sched, bool ALIGN_EPI = false, bool SP2 = false>
; __device__ __forceinline__ void gemm_phase(PG8_LAS unsigned char* lds, const Gemm g, const Sched& S, const Epi& E, const int tid) {
;     const int wid = __builtin_amdgcn_readfirstlane(tid >> 6), lane = tid & 63, wr = wid >> 2, wc = wid & 3, fr = lane & 15, fq = lane >> 4;
;     const int K = g.K, nt = K / BK;
;     unsigned voffA[2], voffB[2];
; #pragma unroll
;     for (int i = 0; i < 2; ++i) { int R, C; stage_rc(tid * 16 + i * 8192, R, C); const int Rb = Epi::PERM ? (2 * (R & ~31) + perm32(R & 31)) : R;
;         voffA[i] = (unsigned)(R * K + C) * 2u; voffB[i] = (unsigned)(Rb * K + C) * 2u; }
;     const size_t kstep = (size_t)(BK * 2);
;     const size_t hstep = (size_t)HALF * K * 2;
;     const size_t tstep = 2 * hstep;
;     const size_t hstepB = Epi::PERM ? (size_t)32 * K * 2 : hstep;
;     const unsigned ldsw = (unsigned)wid * 1024u;
;     const int aoff = lds_byte(wr * 64 + fr, fq * 8), boff = lds_byte(wc * 32 + fr, fq * 8);
;     ...
;     Unit cur, nxt; int ui = 0;
;     if (!S.next(0, cur)) return;
;     f32x4 acc[2][2][4][2];
;     u32x4 iw_[Epi::HAS_INIT ? 16 : 1];
;     if constexpr (Epi::HAS_INIT) E.init_issue(iw_, cur, wr, wc, fr, fq);
;     else {
; #pragma unroll
;     for (int a = 0; a < 2; ++a)
; #pragma unroll
;         for (int b = 0; b < 2; ++b)
; #pragma unroll
;             for (int m = 0; m < 4; ++m)
; #pragma unroll
;                 for (int n = 0; n < 2; ++n) acc[a][b][m][n] = (f32x4){0.f, 0.f, 0.f, 0.f};
;     }
;     bf16x8 At[4][2], B0[2][2], B1[2][2];
;     const char* cA = (const char*)g.A + (size_t)cur.pm * tstep; const char* cB = (const char*)g.Bt + (size_t)cur.pn * tstep;
;     S.a_ready(cur);
;     if constexpr (SP2) {
;         PG8_STAGE(PG8_SB(0, 0), cB, voffB); PG8_STAGE(PG8_SB(0, 1), cB + hstepB, voffB); PG8_STAGE(PG8_SA(0, 0), cA, voffA); PG8_STAGE(PG8_SA(0, 1), cA + hstep, voffA);
;         if (wr == 1) PG8_BAR;
.LBB0_1451:
	v_ashrrev_i32_e32 v5, 31, v3
	v_lshrrev_b32_e32 v5, 26, v5
	v_add_u32_e32 v5, v3, v5
	v_ashrrev_i32_e32 v142, 6, v5
	v_bfe_i32 v5, v3, 27, 1
	v_lshlrev_b32_e32 v4, 4, v3
	v_lshrrev_b32_e32 v5, 22, v5
	v_add_u32_e32 v5, v4, v5
	v_and_b32_e32 v5, 0xfffffc00, v5
	s_ashr_i32 s42, s14, 6
	v_sub_u32_e32 v5, v4, v5
	s_waitcnt lgkmcnt(0)
	s_add_u32 s0, s12, s0
	v_lshrrev_b32_e32 v6, 4, v5
	s_addc_u32 s1, s13, s1
	v_bitop3_b32 v5, v6, v5, 32 bitop3:0x6c
	s_add_u32 s10, s0, 0x4100000
	v_ashrrev_i32_e32 v7, 31, v5
	s_addc_u32 s11, s1, 0
	v_lshrrev_b32_e32 v7, 26, v7
	s_add_u32 s6, s12, 0x17100000
	v_add_u32_e32 v7, v5, v7
	s_addc_u32 s7, s13, 0
	v_lshlrev_b32_e32 v6, 3, v142
	v_ashrrev_i32_e32 v143, 6, v7
	v_and_b32_e32 v7, 0xc0, v7
	s_add_u32 s8, s12, 0xc300000
	v_and_b32_e32 v6, -16, v6
	v_sub_u32_e32 v5, v5, v7
	s_addc_u32 s9, s13, 0
	v_add_u32_e32 v133, v143, v6
	v_lshlrev_b32_e32 v6, 5, v142
	v_ashrrev_i16_sdwa v5, v205, sext(v5) dst_sel:DWORD dst_unused:UNUSED_PAD src0_sel:DWORD src1_sel:BYTE_0
	s_add_u32 s0, s12, 0x2e200000
	v_and_b32_e32 v6, 32, v6
	v_bfe_i32 v144, v5, 0, 16
	v_lshrrev_b32_e32 v5, 2, v133
	s_addc_u32 s1, s13, 0
	v_add_u32_e32 v132, v6, v144
	v_lshlrev_b32_e32 v155, 1, v133
	v_and_b32_e32 v153, 4, v5
	v_and_b32_e32 v154, 3, v143
	v_and_b32_e32 v152, 15, v3
	s_andn2_b64 vcc, exec, s[4:5]
	s_lshl_b32 s43, s42, 10
	s_cbranch_vccnz .LBB0_1499
	v_and_b32_e32 v5, 0x7ffd8, v155
	v_or3_b32 v5, v154, v5, v153
	v_lshlrev_b32_e32 v6, 1, v132
	v_add_u32_e32 v4, 0x2000, v4
	v_lshl_add_u32 v136, v5, 13, v6
	v_ashrrev_i32_e32 v5, 31, v4
	v_lshrrev_b32_e32 v5, 22, v5
	v_add_u32_e32 v5, v4, v5
	v_ashrrev_i32_e32 v145, 10, v5
	v_mul_i32_i24_e32 v5, 0x400, v145
	v_sub_u32_e32 v4, v4, v5
	v_lshrrev_b32_e32 v5, 4, v4
	v_bitop3_b32 v4, v5, v4, 32 bitop3:0x6c
	v_lshl_add_u32 v134, v133, 13, v6
	v_ashrrev_i32_e32 v6, 31, v4
	v_lshrrev_b32_e32 v6, 26, v6
	v_add_u32_e32 v6, v4, v6
	v_lshlrev_b32_e32 v5, 3, v145
	v_ashrrev_i32_e32 v147, 6, v6
	v_and_b32_e32 v6, 0xc0, v6
	v_and_b32_e32 v5, -16, v5
	v_sub_u32_e32 v4, v4, v6
	v_add_u32_e32 v5, v147, v5
	v_ashrrev_i16_sdwa v4, v205, sext(v4) dst_sel:DWORD dst_unused:UNUSED_PAD src0_sel:DWORD src1_sel:BYTE_0
	v_lshlrev_b32_e32 v7, 5, v145
	v_bfe_i32 v148, v4, 0, 16
	v_lshlrev_b32_e32 v4, 1, v5
	v_lshrrev_b32_e32 v6, 2, v5
	s_ashr_i32 s5, s14, 8
	v_and_b32_e32 v7, 32, v7
	v_and_b32_e32 v6, 4, v6
	v_and_b32_e32 v8, 3, v147
	v_and_b32_e32 v4, 0x7ffd8, v4
	s_lshl_b32 s15, s5, 6
	s_lshl_b32 s12, s28, 8
	s_and_b32 s4, s42, 3
	v_or3_b32 v4, v8, v6, v4
	v_add_lshl_u32 v6, v7, v148, 1
	s_add_i32 s12, s12, s15
	v_bfe_u32 v146, v3, 4, 2
	v_lshl_add_u32 v140, v4, 13, v6
	v_or_b32_e32 v4, s12, v152
	s_lshl_b32 s12, s24, 8
	s_lshl_b32 s54, s4, 6
	v_lshlrev_b32_e32 v156, 3, v146
	s_or_b32 s12, s12, s54
	v_or_b32_e32 v10, 16, v4
	v_lshl_add_u32 v138, v5, 13, v6
	v_or_b32_e32 v6, s12, v156
	v_ashrrev_i32_e32 v5, 31, v4
	v_ashrrev_i32_e32 v11, 31, v10
	v_lshlrev_b64 v[8:9], 11, v[4:5]
	v_ashrrev_i32_e32 v7, 31, v6
	v_lshlrev_b64 v[10:11], 11, v[10:11]
	v_lshl_add_u64 v[8:9], s[8:9], 0, v[8:9]
	v_lshlrev_b64 v[6:7], 1, v[6:7]
	v_lshl_add_u64 v[10:11], s[8:9], 0, v[10:11]
	v_lshl_add_u64 v[8:9], v[8:9], 0, v[6:7]
	v_lshl_add_u64 v[10:11], v[10:11], 0, v[6:7]
	global_load_dwordx4 v[64:67], v[8:9], off
	global_load_dwordx4 v[56:59], v[8:9], off offset:64
	global_load_dwordx4 v[60:63], v[10:11], off
	global_load_dwordx4 v[48:51], v[10:11], off offset:64
	v_or_b32_e32 v10, 32, v4
	v_or_b32_e32 v4, 48, v4
	v_ashrrev_i32_e32 v11, 31, v10
	v_ashrrev_i32_e32 v5, 31, v4
	v_lshlrev_b64 v[10:11], 11, v[10:11]
	v_lshlrev_b64 v[4:5], 11, v[4:5]
	v_lshl_add_u64 v[10:11], s[8:9], 0, v[10:11]
	v_lshl_add_u64 v[4:5], s[8:9], 0, v[4:5]
	v_lshl_add_u64 v[10:11], v[10:11], 0, v[6:7]
	v_lshl_add_u64 v[4:5], v[4:5], 0, v[6:7]
	v_add_co_u32_e32 v6, vcc, s57, v8
	global_load_dwordx4 v[52:55], v[10:11], off
	global_load_dwordx4 v[40:43], v[10:11], off offset:64
	v_addc_co_u32_e32 v7, vcc, 0, v9, vcc
	global_load_dwordx4 v[44:47], v[4:5], off
	global_load_dwordx4 v[36:39], v[4:5], off offset:64
	v_lshl_add_u64 v[4:5], v[8:9], 0, s[50:51]
	global_load_dwordx4 v[32:35], v[6:7], off
	global_load_dwordx4 v[28:31], v[4:5], off offset:64
	v_add_co_u32_e32 v6, vcc, s26, v8
	s_mov_b32 s12, 0x50000
	s_nop 0
	v_addc_co_u32_e32 v7, vcc, 0, v9, vcc
	v_lshl_add_u64 v[4:5], v[8:9], 0, s[72:73]
	global_load_dwordx4 v[24:27], v[6:7], off
	global_load_dwordx4 v[20:23], v[4:5], off offset:64
	v_add_co_u32_e32 v6, vcc, s12, v8
	s_mov_b64 s[12:13], 0x58000
	s_nop 0
	v_addc_co_u32_e32 v7, vcc, 0, v9, vcc
	v_lshl_add_u64 v[16:17], v[8:9], 0, s[12:13]
	s_mov_b32 s12, 0x58000
	s_ashr_i32 s29, s28, 31
	s_ashr_i32 s25, s24, 31
	v_lshl_add_u64 v[4:5], v[8:9], 0, s[74:75]
	v_add_co_u32_e32 v8, vcc, s12, v8
	s_lshl_b64 s[12:13], s[28:29], 21
	s_lshl_b64 s[16:17], s[24:25], 21
	s_lshr_b32 s92, s2, 3
	s_lshr_b32 s99, s2, 6
	s_add_i32 s92, s92, s99
	s_and_b32 s92, s92, 3
	s_lshl_b32 s92, s92, 8
	s_add_u32 s36, s10, s16
	s_addc_u32 s37, s11, s17
	s_add_u32 s36, s36, s92
	s_addc_u32 s37, s37, 0
	s_add_i32 s29, s43, 0
	v_addc_co_u32_e32 v9, vcc, 0, v9, vcc
	s_add_i32 m0, s29, 0x10000
	global_load_dwordx4 v[12:15], v[6:7], off
	s_nop 0
	global_load_dwordx4 v[4:7], v[4:5], off offset:64
	s_nop 0
	global_load_dwordx4 v[8:11], v[8:9], off
	s_nop 0
	global_load_dwordx4 v[16:19], v[16:17], off offset:64
	v_mov_b32_e32 v137, v2
	global_load_lds_dwordx4 v136, s[36:37]
	s_add_i32 m0, s29, 0x12000
	s_add_u32 s16, s36, 0x40000
	global_load_lds_dwordx4 v140, s[36:37]
	s_addc_u32 s17, s37, 0
	s_add_i32 m0, s29, 0x14000
	v_mov_b32_e32 v141, v2
	global_load_lds_dwordx4 v136, s[16:17]
	s_add_i32 m0, s29, 0x16000
	s_add_u32 s38, s6, s12
	s_addc_u32 s39, s7, s13
	s_add_u32 s38, s38, s92
	s_addc_u32 s39, s39, 0
	s_add_i32 s55, s29, 0x2000
	global_load_lds_dwordx4 v140, s[16:17]
	s_mov_b32 m0, s29
	s_add_u32 s12, s38, 0x100000
	global_load_lds_dwordx4 v134, s[38:39]
	s_mov_b32 m0, s55
	s_addc_u32 s13, s39, 0
	s_add_i32 s62, s29, 0x4000
	global_load_lds_dwordx4 v138, s[38:39]
	s_mov_b32 m0, s62
	s_add_i32 s63, s29, 0x6000
	global_load_lds_dwordx4 v134, s[12:13]
	s_mov_b32 m0, s63
	v_mov_b32_e32 v135, v2
	global_load_lds_dwordx4 v138, s[12:13]
	v_mov_b32_e32 v139, v2
	s_cmp_eq_u32 s5, 1
	v_lshl_add_u64 v[74:75], s[36:37], 0, v[136:137]
	v_lshl_add_u64 v[72:73], s[36:37], 0, v[140:141]
	v_lshl_add_u64 v[68:69], s[38:39], 0, v[134:135]
	s_cselect_b64 s[12:13], -1, 0
	s_cmp_lg_u32 s5, 1
	v_lshl_add_u64 v[70:71], s[38:39], 0, v[138:139]
	s_cbranch_scc1 .LBB0_1454
	s_barrier
; DI float bf_lo(unsigned u) { return __uint_as_float(u << 16); }
; DI float bf_hi(unsigned u) { return __uint_as_float(u & 0xffff0000u); }
; #define PG8_STAGE(bufoff, gbase, voff) do { _Pragma("unroll") for (int _i = 0; _i < 2; ++_i) \
;         __builtin_amdgcn_global_load_lds((const unsigned*)((const char*)(gbase) + (voff)[_i]), (PG8_LAS unsigned*)(lds + (bufoff) + ldsw + _i * 8192), 16, 0, 0); } while (0)
; #define PG8_WAIT_V(n) asm volatile("s_waitcnt vmcnt(" #n ")" ::: "memory")
; #define PG8_BAR __builtin_amdgcn_s_barrier()
;     DI void init_finish(f32x4 (&acc)[2][2][4][2], const u32x4 (&w)[R8::HAS_PRE ? 16 : 1]) const {
;         if constexpr (R8::HAS_PRE) {
; #pragma unroll
;             for (int ai = 0; ai < 2; ++ai)
; #pragma unroll
;                 for (int m = 0; m < 4; ++m)
; #pragma unroll
;                     for (int bj = 0; bj < 2; ++bj) { const u32x4 v = w[(ai * 4 + m) * 2 + bj];
;                         acc[ai][bj][m][0] = (f32x4){bf_lo(v.x), bf_hi(v.x), bf_lo(v.y), bf_hi(v.y)}; acc[ai][bj][m][1] = (f32x4){bf_lo(v.z), bf_hi(v.z), bf_lo(v.w), bf_hi(v.w)}; }
;         }
;     }
; template <class Epi, class Sched, bool ALIGN_EPI = false, bool SP2 = false>
; __device__ __forceinline__ void gemm_phase(PG8_LAS unsigned char* lds, const Gemm g, const Sched& S, const Epi& E, const int tid) {
;     ...
;         if (wr == 1) PG8_BAR;
;         PG8_WAIT_V(2); PG8_BAR;
;         PG8_STAGE(PG8_SB(1, 0), cB + kstep, voffB); PG8_STAGE(PG8_SA(1, 0), cA + kstep, voffA); PG8_STAGE(PG8_SB(1, 1), cB + hstepB + kstep, voffB);
;         PG8_WAIT_V(6); PG8_BAR;
;     } else {
;         PG8_STAGE(PG8_SB(0, 0), cB, voffB); PG8_STAGE(PG8_SA(0, 0), cA, voffA); PG8_STAGE(PG8_SB(0, 1), cB + hstepB, voffB); PG8_STAGE(PG8_SA(0, 1), cA + hstep, voffA);
;         if (wr == 1) PG8_BAR;
;         PG8_WAIT_V(4); PG8_BAR;
;         PG8_STAGE(PG8_SB(1, 0), cB + kstep, voffB); PG8_STAGE(PG8_SA(1, 0), cA + kstep, voffA); PG8_STAGE(PG8_SB(1, 1), cB + hstepB + kstep, voffB);
;         PG8_WAIT_V(6); PG8_BAR;
;     }
;     if constexpr (Epi::HAS_INIT) E.init_finish(acc, iw_);
.LBB0_1454:
	v_or_b32_e32 v157, s15, v152
	v_lshlrev_b32_e32 v76, 6, v157
	v_lshlrev_b32_e32 v77, 4, v146
	s_movk_i32 s15, 0x3c0
	v_lshlrev_b32_e32 v78, 2, v157
	v_and_or_b32 v76, v76, s15, v77
	s_lshl_b32 s5, s5, 13
	v_and_b32_e32 v78, 32, v78
	v_bitop3_b32 v149, v76, s5, v78 bitop3:0xde
	v_lshl_or_b32 v76, v152, 6, v77
	v_lshlrev_b32_e32 v77, 2, v152
	s_add_i32 m0, s29, 0x18000
	v_lshl_add_u64 v[74:75], v[74:75], 0, s[52:53]
	s_lshl_b32 s4, s4, 12
	v_and_b32_e32 v77, 32, v77
	s_waitcnt vmcnt(2)
	s_barrier
	global_load_lds_dwordx4 v[74:75], off
	v_lshl_add_u64 v[72:73], v[72:73], 0, s[52:53]
	s_add_i32 m0, s29, 0x1a000
	s_add_i32 s64, s29, 0x8000
	s_add_i32 s65, s29, 0xa000
	v_bitop3_b32 v158, v76, s4, v77 bitop3:0xde
	global_load_lds_dwordx4 v[72:73], off
	v_lshl_add_u64 v[68:69], v[68:69], 0, s[52:53]
	s_mov_b32 m0, s64
	s_add_u32 s4, s36, 0x40080
	global_load_lds_dwordx4 v[68:69], off
	v_lshl_add_u64 v[68:69], v[70:71], 0, s[52:53]
	s_mov_b32 m0, s65
	s_addc_u32 s5, s37, 0
	global_load_lds_dwordx4 v[68:69], off
	s_add_i32 m0, s29, 0x1c000
	v_lshl_add_u64 v[68:69], s[4:5], 0, v[136:137]
	global_load_lds_dwordx4 v[68:69], off
	v_lshl_add_u64 v[68:69], s[4:5], 0, v[140:141]
	s_add_i32 m0, s29, 0x1e000
	v_cmp_eq_u32_e64 s[4:5], 0, v146
	global_load_lds_dwordx4 v[68:69], off
	v_lshlrev_b32_e32 v146, 16, v142
	v_and_b32_e32 v146, 0xfffe0000, v146
	v_lshl_add_u32 v143, v143, 13, v146
	v_and_b32_e32 v142, 1, v142
	v_lshl_or_b32 v142, v142, 6, v143
	v_lshl_add_u32 v142, v144, 1, v142
	v_lshlrev_b32_e32 v144, 16, v145
	v_and_b32_e32 v144, 0xfffe0000, v144
	s_waitcnt vmcnt(6)
	v_lshl_add_u32 v144, v147, 13, v144
	v_and_b32_e32 v145, 1, v145
	s_cmpk_lt_u32 s14, 0x100
	v_lshl_or_b32 v144, v145, 6, v144
	s_waitcnt vmcnt(0)
	v_lshlrev_b32_e32 v120, 16, v64
	v_and_b32_e32 v121, 0xffff0000, v64
	v_lshlrev_b32_e32 v122, 16, v65
	v_and_b32_e32 v123, 0xffff0000, v65
	v_lshlrev_b32_e32 v128, 16, v66
	v_and_b32_e32 v129, 0xffff0000, v66
	v_lshlrev_b32_e32 v130, 16, v67
	v_and_b32_e32 v131, 0xffff0000, v67
	v_lshlrev_b32_e32 v116, 16, v56
	v_and_b32_e32 v117, 0xffff0000, v56
	v_lshlrev_b32_e32 v118, 16, v57
	v_and_b32_e32 v119, 0xffff0000, v57
	v_lshlrev_b32_e32 v124, 16, v58
	v_and_b32_e32 v125, 0xffff0000, v58
	v_lshlrev_b32_e32 v126, 16, v59
	v_and_b32_e32 v127, 0xffff0000, v59
	v_lshlrev_b32_e32 v100, 16, v60
	v_and_b32_e32 v101, 0xffff0000, v60
	v_lshlrev_b32_e32 v102, 16, v61
	v_and_b32_e32 v103, 0xffff0000, v61
	v_lshlrev_b32_e32 v108, 16, v62
	v_and_b32_e32 v109, 0xffff0000, v62
	v_lshlrev_b32_e32 v110, 16, v63
	v_and_b32_e32 v111, 0xffff0000, v63
	v_lshlrev_b32_e32 v104, 16, v48
	v_and_b32_e32 v105, 0xffff0000, v48
	v_lshlrev_b32_e32 v106, 16, v49
	v_and_b32_e32 v107, 0xffff0000, v49
	v_lshlrev_b32_e32 v112, 16, v50
	v_and_b32_e32 v113, 0xffff0000, v50
	v_lshlrev_b32_e32 v114, 16, v51
	v_and_b32_e32 v115, 0xffff0000, v51
	v_lshlrev_b32_e32 v84, 16, v52
	v_and_b32_e32 v85, 0xffff0000, v52
	v_lshlrev_b32_e32 v86, 16, v53
	v_and_b32_e32 v87, 0xffff0000, v53
	v_lshlrev_b32_e32 v92, 16, v54
	v_and_b32_e32 v93, 0xffff0000, v54
	v_lshlrev_b32_e32 v94, 16, v55
	v_and_b32_e32 v95, 0xffff0000, v55
	v_lshlrev_b32_e32 v88, 16, v40
	v_and_b32_e32 v89, 0xffff0000, v40
	v_lshlrev_b32_e32 v90, 16, v41
	v_and_b32_e32 v91, 0xffff0000, v41
	v_lshlrev_b32_e32 v96, 16, v42
	v_and_b32_e32 v97, 0xffff0000, v42
	v_lshlrev_b32_e32 v98, 16, v43
	v_and_b32_e32 v99, 0xffff0000, v43
	v_lshlrev_b32_e32 v68, 16, v44
	v_and_b32_e32 v69, 0xffff0000, v44
	v_lshlrev_b32_e32 v70, 16, v45
	v_and_b32_e32 v71, 0xffff0000, v45
	v_lshlrev_b32_e32 v76, 16, v46
	v_and_b32_e32 v77, 0xffff0000, v46
	v_lshlrev_b32_e32 v78, 16, v47
	v_and_b32_e32 v79, 0xffff0000, v47
	v_lshlrev_b32_e32 v72, 16, v36
	v_and_b32_e32 v73, 0xffff0000, v36
	v_lshlrev_b32_e32 v74, 16, v37
	v_and_b32_e32 v75, 0xffff0000, v37
	v_lshlrev_b32_e32 v80, 16, v38
	v_and_b32_e32 v81, 0xffff0000, v38
	v_lshlrev_b32_e32 v82, 16, v39
	v_and_b32_e32 v83, 0xffff0000, v39
	v_lshlrev_b32_e32 v52, 16, v32
	v_and_b32_e32 v53, 0xffff0000, v32
	v_lshlrev_b32_e32 v54, 16, v33
	v_and_b32_e32 v55, 0xffff0000, v33
	v_lshlrev_b32_e32 v60, 16, v34
	v_and_b32_e32 v61, 0xffff0000, v34
	v_lshlrev_b32_e32 v62, 16, v35
	v_and_b32_e32 v63, 0xffff0000, v35
	v_lshlrev_b32_e32 v56, 16, v28
	v_and_b32_e32 v57, 0xffff0000, v28
	v_lshlrev_b32_e32 v58, 16, v29
	v_and_b32_e32 v59, 0xffff0000, v29
	v_lshlrev_b32_e32 v64, 16, v30
	v_and_b32_e32 v65, 0xffff0000, v30
	v_lshlrev_b32_e32 v66, 16, v31
	v_and_b32_e32 v67, 0xffff0000, v31
	v_lshlrev_b32_e32 v36, 16, v24
	v_and_b32_e32 v37, 0xffff0000, v24
	v_lshlrev_b32_e32 v38, 16, v25
	v_and_b32_e32 v39, 0xffff0000, v25
	v_lshlrev_b32_e32 v44, 16, v26
	v_and_b32_e32 v45, 0xffff0000, v26
	v_lshlrev_b32_e32 v46, 16, v27
	v_and_b32_e32 v47, 0xffff0000, v27
	v_lshlrev_b32_e32 v40, 16, v20
	v_and_b32_e32 v41, 0xffff0000, v20
	v_lshlrev_b32_e32 v42, 16, v21
	v_and_b32_e32 v43, 0xffff0000, v21
	v_lshlrev_b32_e32 v48, 16, v22
	v_and_b32_e32 v49, 0xffff0000, v22
	v_lshlrev_b32_e32 v50, 16, v23
	v_and_b32_e32 v51, 0xffff0000, v23
	v_lshlrev_b32_e32 v20, 16, v12
	v_and_b32_e32 v21, 0xffff0000, v12
	v_lshlrev_b32_e32 v22, 16, v13
	v_and_b32_e32 v23, 0xffff0000, v13
	v_lshlrev_b32_e32 v28, 16, v14
	v_and_b32_e32 v29, 0xffff0000, v14
	v_lshlrev_b32_e32 v30, 16, v15
	v_and_b32_e32 v31, 0xffff0000, v15
	v_lshlrev_b32_e32 v24, 16, v4
	v_and_b32_e32 v25, 0xffff0000, v4
	v_lshlrev_b32_e32 v26, 16, v5
	v_and_b32_e32 v27, 0xffff0000, v5
	v_lshlrev_b32_e32 v32, 16, v6
	v_and_b32_e32 v33, 0xffff0000, v6
	v_lshlrev_b32_e32 v34, 16, v7
	v_and_b32_e32 v35, 0xffff0000, v7
	v_lshlrev_b32_e32 v4, 16, v8
	v_and_b32_e32 v5, 0xffff0000, v8
	v_lshlrev_b32_e32 v6, 16, v9
	v_and_b32_e32 v7, 0xffff0000, v9
	v_lshlrev_b32_e32 v12, 16, v10
	v_and_b32_e32 v13, 0xffff0000, v10
	v_lshlrev_b32_e32 v14, 16, v11
	v_and_b32_e32 v15, 0xffff0000, v11
	v_lshlrev_b32_e32 v8, 16, v16
	v_and_b32_e32 v9, 0xffff0000, v16
	v_lshlrev_b32_e32 v10, 16, v17
	v_and_b32_e32 v11, 0xffff0000, v17
	v_lshlrev_b32_e32 v16, 16, v18
	v_and_b32_e32 v17, 0xffff0000, v18
	v_lshlrev_b32_e32 v18, 16, v19
	v_and_b32_e32 v19, 0xffff0000, v19
	s_cselect_b64 s[14:15], -1, 0
	s_mov_b32 s66, 0
	s_lshl_b32 s67, s27, 3
	v_or_b32_e32 v159, s54, v156
	v_mov_b32_e32 v143, v2
	v_lshl_add_u32 v144, v148, 1, v144
	v_mov_b32_e32 v145, v2
	v_add_u32_e32 v160, 0, v149
	s_barrier
	s_sub_u32 s36, s36, s92
	s_subb_u32 s37, s37, 0
	s_sub_u32 s38, s38, s92
	s_subb_u32 s39, s39, 0
	s_branch .LBB0_1457

;     DI bool next(int i, Unit& u) const { const int L = i * 32 + rank; if (L >= ppg * nN) return false; u.pm = ppg * grp + (L % ppg); const int p0 = L / ppg, p1 = p0 + rot; u.pn = rev ? nN - 1 - p0 : (p1 >= nN ? p1 - nN : p1); return true; }
; #define PG8_STAGE(bufoff, gbase, voff) do { _Pragma("unroll") for (int _i = 0; _i < 2; ++_i) \
;         __builtin_amdgcn_global_load_lds((const unsigned*)((const char*)(gbase) + (voff)[_i]), (PG8_LAS unsigned*)(lds + (bufoff) + ldsw + _i * 8192), 16, 0, 0); } while (0)
; #define PG8_LDA(dst, b, h) do { _Pragma("unroll") for (int m = 0; m < 4; ++m) _Pragma("unroll") for (int k = 0; k < 2; ++k) dst[m][k] = *(const PG8_LAS bf16x8*)(lds + PG8_SA(b, h) + aoff + m * 2048 + k * 1024); } while (0)
; #define PG8_LDB(dst, b, h) do { _Pragma("unroll") for (int n = 0; n < 2; ++n) _Pragma("unroll") for (int k = 0; k < 2; ++k) dst[n][k] = *(const PG8_LAS bf16x8*)(lds + PG8_SB(b, h) + boff + n * 2048 + k * 1024); } while (0)
; #define PG8_BAR __builtin_amdgcn_s_barrier()
; template <class Epi, class Sched, bool ALIGN_EPI = false, bool SP2 = false>
; __device__ __forceinline__ void gemm_phase(PG8_LAS unsigned char* lds, const Gemm g, const Sched& S, const Epi& E, const int tid) {
;     ...
;         const bool has_next = S.next(ui + 1, nxt);
;         const char* nA = has_next ? (const char*)g.A + (size_t)nxt.pm * tstep : cA; const char* nB = has_next ? (const char*)g.Bt + (size_t)nxt.pn * tstep : cB;
;         for (int t = 0; t < nt; t += 2) {
;             const bool last = (t == nt - 2);
;             const char* a1 = cA + (size_t)(t + 1) * kstep;
;             const char* a2 = last ? nA : cA + (size_t)(t + 2) * kstep; const char* b2 = last ? nB : cB + (size_t)(t + 2) * kstep;
;             const char* a3 = a2 + kstep; const char* b3 = b2 + kstep;
;             if (last && has_next) S.a_ready(nxt);
;             if constexpr (SP2) {
;             PG8_LDB(B0, 0, 0); PG8_LDB(B1, 0, 1); PG8_SCHED; PG8_LDA(At, 0, 0); PG8_STAGE(PG8_SA(1, 1), a1 + hstep, voffA);
;             PG8_WAIT_V(8); PG8_WAIT_L(0); PG8_BAR; PG8_MMA(0, 0, At, B0); PG8_MMA(0, 1, At, B1); PG8_BAR; PG8_SCHED;
;             PG8_LDA(At, 0, 1); PG8_STAGE(PG8_SB(0, 0), b2, voffB); PG8_STAGE(PG8_SB(0, 1), b2 + hstepB, voffB); PG8_STAGE(PG8_SA(0, 0), a2, voffA);
;             PG8_WAIT_V(8); PG8_WAIT_L(0); PG8_BAR; PG8_MMA(1, 0, At, B0); PG8_MMA(1, 1, At, B1); PG8_BAR; PG8_SCHED;
.LBB0_1459:
	s_ashr_i32 s19, s18, 31
	s_lshl_b64 s[20:21], s[18:19], 21
	s_add_u32 s20, s6, s20
	s_addc_u32 s21, s7, s21
	s_and_b64 s[22:23], s[30:31], exec
	s_cselect_b32 s19, s21, s39
	s_cselect_b32 s25, s20, s38
	s_add_u32 s25, s25, s92
	s_addc_u32 s19, s19, 0
	s_ashr_i32 s17, s16, 31
	s_lshl_b64 s[22:23], s[16:17], 21
	s_add_u32 s22, s10, s22
	s_addc_u32 s23, s11, s23
	s_and_b64 s[40:41], s[30:31], exec
	s_cselect_b32 s17, s23, s37
	s_cselect_b32 s76, s22, s36
	s_add_u32 s76, s76, s92
	s_addc_u32 s17, s17, 0
	s_add_u32 s38, s38, 0x100080
	s_addc_u32 s39, s39, 0
	s_mov_b32 s78, s36
	s_mov_b32 s79, s37
	s_mov_b32 s80, -2
.LBB0_1460:
	s_lshl_b32 s100, s80, 7
	s_add_i32 s100, s100, s92
	s_add_i32 s100, s100, 0x100
	s_add_i32 s99, s100, 0x100
	s_and_b32 s100, s100, 0x1f00
	s_and_b32 s99, s99, 0x1f00
	s_add_u32 s100, s38, s100
	s_addc_u32 s101, s39, 0
	s_add_u32 s36, s38, 0xffefff80
	s_addc_u32 s37, s39, -1
	s_add_u32 s36, s36, s99
	s_addc_u32 s37, s37, 0
	s_add_i32 s81, 0, 0x10000
	s_cmp_eq_u32 s80, 60
	s_cselect_b32 s41, s19, s37
	s_cselect_b32 s40, s25, s36
	v_add_u32_e32 v150, s81, v158
	s_add_u32 s36, s78, s99
	s_addc_u32 s37, s79, 0
	s_cmp_eq_u32 s80, 60
	s_cselect_b32 s37, s17, s37
	s_cselect_b32 s36, s76, s36
	s_cmp_eq_u32 s80, 60
	s_cselect_b32 s32, 1, 0
	s_andn2_b32 s32, s32, s30
	s_add_i32 s84, 0, 0x14000
	ds_read_b128 v[146:149], v150
	ds_read_b128 v[162:165], v150 offset:1024
	ds_read_b128 v[170:173], v150 offset:2048
	ds_read_b128 v[174:177], v150 offset:3072
	v_add_u32_e32 v150, s84, v158
	ds_read_b128 v[178:181], v150
	ds_read_b128 v[182:185], v150 offset:1024
	ds_read_b128 v[186:189], v150 offset:2048
	ds_read_b128 v[190:193], v150 offset:3072
	v_lshl_add_u64 v[150:151], s[100:101], 0, v[142:143]
	s_add_i32 m0, s29, 0xc000
	ds_read_b128 v[194:197], v160
	ds_read_b128 v[198:201], v160 offset:1024
	ds_read_b128 v[212:215], v160 offset:2048
	ds_read_b128 v[216:219], v160 offset:3072
	ds_read_b128 v[220:223], v160 offset:4096
	ds_read_b128 v[224:227], v160 offset:5120
	ds_read_b128 v[228:231], v160 offset:6144
	ds_read_b128 v[232:235], v160 offset:7168
	global_load_lds_dwordx4 v[150:151], off
	v_lshl_add_u64 v[150:151], s[100:101], 0, v[144:145]
	s_add_i32 m0, s29, 0xe000
	s_nop 0
	global_load_lds_dwordx4 v[150:151], off
	s_waitcnt vmcnt(8)
	s_waitcnt lgkmcnt(0)
	s_barrier
	s_setprio 1
	s_waitcnt lgkmcnt(0)
	v_mfma_f32_16x16x32_bf16 v[120:123], v[146:149], v[194:197], v[120:123]
	v_mfma_f32_16x16x32_bf16 v[128:131], v[170:173], v[194:197], v[128:131]
	v_mfma_f32_16x16x32_bf16 v[100:103], v[146:149], v[212:215], v[100:103]
	v_mfma_f32_16x16x32_bf16 v[108:111], v[170:173], v[212:215], v[108:111]
	v_mfma_f32_16x16x32_bf16 v[84:87], v[146:149], v[220:223], v[84:87]
	v_mfma_f32_16x16x32_bf16 v[92:95], v[170:173], v[220:223], v[92:95]
	v_mfma_f32_16x16x32_bf16 v[68:71], v[146:149], v[228:231], v[68:71]
	v_mfma_f32_16x16x32_bf16 v[76:79], v[170:173], v[228:231], v[76:79]
	v_mfma_f32_16x16x32_bf16 v[120:123], v[162:165], v[198:201], v[120:123]
	v_mfma_f32_16x16x32_bf16 v[128:131], v[174:177], v[198:201], v[128:131]
	v_mfma_f32_16x16x32_bf16 v[100:103], v[162:165], v[216:219], v[100:103]
	v_mfma_f32_16x16x32_bf16 v[108:111], v[174:177], v[216:219], v[108:111]
	v_mfma_f32_16x16x32_bf16 v[84:87], v[162:165], v[224:227], v[84:87]
	v_mfma_f32_16x16x32_bf16 v[92:95], v[174:177], v[224:227], v[92:95]
	v_mfma_f32_16x16x32_bf16 v[68:71], v[162:165], v[232:235], v[68:71]
	v_mfma_f32_16x16x32_bf16 v[76:79], v[174:177], v[232:235], v[76:79]
	s_setprio 0
	s_setprio 1
	v_mfma_f32_16x16x32_bf16 v[116:119], v[178:181], v[194:197], v[116:119]
	v_mfma_f32_16x16x32_bf16 v[124:127], v[186:189], v[194:197], v[124:127]
	v_mfma_f32_16x16x32_bf16 v[104:107], v[178:181], v[212:215], v[104:107]
	v_mfma_f32_16x16x32_bf16 v[112:115], v[186:189], v[212:215], v[112:115]
	v_mfma_f32_16x16x32_bf16 v[88:91], v[178:181], v[220:223], v[88:91]
	v_mfma_f32_16x16x32_bf16 v[96:99], v[186:189], v[220:223], v[96:99]
	v_mfma_f32_16x16x32_bf16 v[72:75], v[178:181], v[228:231], v[72:75]
	v_mfma_f32_16x16x32_bf16 v[80:83], v[186:189], v[228:231], v[80:83]
	v_mfma_f32_16x16x32_bf16 v[116:119], v[182:185], v[198:201], v[116:119]
	v_mfma_f32_16x16x32_bf16 v[124:127], v[190:193], v[198:201], v[124:127]
	v_mfma_f32_16x16x32_bf16 v[104:107], v[182:185], v[216:219], v[104:107]
	v_mfma_f32_16x16x32_bf16 v[112:115], v[190:193], v[216:219], v[112:115]
	v_mfma_f32_16x16x32_bf16 v[88:91], v[182:185], v[224:227], v[88:91]
	v_mfma_f32_16x16x32_bf16 v[96:99], v[190:193], v[224:227], v[96:99]
	v_mfma_f32_16x16x32_bf16 v[72:75], v[182:185], v[232:235], v[72:75]
	v_mfma_f32_16x16x32_bf16 v[80:83], v[190:193], v[232:235], v[80:83]
	s_setprio 0
	s_barrier
	s_add_i32 s81, s81, s43
	v_lshl_add_u64 v[150:151], s[36:37], 0, v[136:137]
	s_mov_b32 m0, s81
	ds_read_b128 v[194:197], v160 offset:16384
	ds_read_b128 v[198:201], v160 offset:17408
	ds_read_b128 v[212:215], v160 offset:18432
	ds_read_b128 v[216:219], v160 offset:19456
	ds_read_b128 v[220:223], v160 offset:20480
	ds_read_b128 v[224:227], v160 offset:21504
	ds_read_b128 v[228:231], v160 offset:22528
	ds_read_b128 v[232:235], v160 offset:23552
	s_cmp_lg_u32 s32, 0
	s_cbranch_scc1 .Lbt1460_0
	global_load_lds_dwordx4 v[150:151], off

; #define PG8_STAGE(bufoff, gbase, voff) do { _Pragma("unroll") for (int _i = 0; _i < 2; ++_i) \
;         __builtin_amdgcn_global_load_lds((const unsigned*)((const char*)(gbase) + (voff)[_i]), (PG8_LAS unsigned*)(lds + (bufoff) + ldsw + _i * 8192), 16, 0, 0); } while (0)
; #define PG8_LDA(dst, b, h) do { _Pragma("unroll") for (int m = 0; m < 4; ++m) _Pragma("unroll") for (int k = 0; k < 2; ++k) dst[m][k] = *(const PG8_LAS bf16x8*)(lds + PG8_SA(b, h) + aoff + m * 2048 + k * 1024); } while (0)
; #define PG8_MMA(ai, bj, At, Bt) do { __builtin_amdgcn_s_setprio(1); _Pragma("unroll") for (int m = 0; m < 4; ++m) _Pragma("unroll") for (int n = 0; n < 2; ++n) _Pragma("unroll") for (int k = 0; k < 2; ++k) \
;         acc[ai][bj][m][n] = __builtin_amdgcn_mfma_f32_16x16x32_bf16(Bt[n][k], At[m][k], acc[ai][bj][m][n], 0, 0, 0); __builtin_amdgcn_s_setprio(0); } while (0)
; #define PG8_WAIT_V(n) asm volatile("s_waitcnt vmcnt(" #n ")" ::: "memory")
; #define PG8_WAIT_L(n) asm volatile("s_waitcnt lgkmcnt(" #n ")" ::: "memory")
; #define PG8_BAR __builtin_amdgcn_s_barrier()
; #define PG8_SCHED __builtin_amdgcn_sched_barrier(0)
; template <class Epi, class Sched, bool ALIGN_EPI = false, bool SP2 = false>
; __device__ __forceinline__ void gemm_phase(PG8_LAS unsigned char* lds, const Gemm g, const Sched& S, const Epi& E, const int tid) {
;     ...
;             PG8_WAIT_V(8); PG8_WAIT_L(0); PG8_BAR; PG8_MMA(0, 0, At, B0); PG8_MMA(0, 1, At, B1); PG8_BAR; PG8_SCHED;
;             PG8_LDA(At, 1, 1); PG8_STAGE(PG8_SB(1, 0), b3, voffB); PG8_STAGE(PG8_SB(1, 1), b3 + hstepB, voffB); PG8_STAGE(PG8_SA(1, 0), a3, voffA);
;             PG8_WAIT_V(8); PG8_WAIT_L(0); PG8_BAR; PG8_MMA(1, 0, At, B0); PG8_MMA(1, 1, At, B1); PG8_BAR; PG8_SCHED;
.Lbt1460_13:
	s_waitcnt vmcnt(8)
	s_waitcnt lgkmcnt(0)
	s_barrier
	s_setprio 1
	s_waitcnt lgkmcnt(0)
	v_mfma_f32_16x16x32_bf16 v[52:55], v[146:149], v[194:197], v[52:55]
	v_mfma_f32_16x16x32_bf16 v[60:63], v[170:173], v[194:197], v[60:63]
	v_mfma_f32_16x16x32_bf16 v[36:39], v[146:149], v[212:215], v[36:39]
	v_mfma_f32_16x16x32_bf16 v[44:47], v[170:173], v[212:215], v[44:47]
	v_mfma_f32_16x16x32_bf16 v[20:23], v[146:149], v[220:223], v[20:23]
	v_mfma_f32_16x16x32_bf16 v[28:31], v[170:173], v[220:223], v[28:31]
	v_mfma_f32_16x16x32_bf16 v[4:7], v[146:149], v[228:231], v[4:7]
	v_mfma_f32_16x16x32_bf16 v[12:15], v[170:173], v[228:231], v[12:15]
	v_mfma_f32_16x16x32_bf16 v[52:55], v[162:165], v[198:201], v[52:55]
	v_mfma_f32_16x16x32_bf16 v[60:63], v[174:177], v[198:201], v[60:63]
	v_mfma_f32_16x16x32_bf16 v[36:39], v[162:165], v[216:219], v[36:39]
	v_mfma_f32_16x16x32_bf16 v[44:47], v[174:177], v[216:219], v[44:47]
	v_mfma_f32_16x16x32_bf16 v[20:23], v[162:165], v[224:227], v[20:23]
	v_mfma_f32_16x16x32_bf16 v[28:31], v[174:177], v[224:227], v[28:31]
	v_mfma_f32_16x16x32_bf16 v[4:7], v[162:165], v[232:235], v[4:7]
	v_mfma_f32_16x16x32_bf16 v[12:15], v[174:177], v[232:235], v[12:15]
	s_setprio 0
	s_setprio 1
	v_mfma_f32_16x16x32_bf16 v[56:59], v[178:181], v[194:197], v[56:59]
	v_mfma_f32_16x16x32_bf16 v[64:67], v[186:189], v[194:197], v[64:67]
	v_mfma_f32_16x16x32_bf16 v[40:43], v[178:181], v[212:215], v[40:43]
	v_mfma_f32_16x16x32_bf16 v[48:51], v[186:189], v[212:215], v[48:51]
	v_mfma_f32_16x16x32_bf16 v[24:27], v[178:181], v[220:223], v[24:27]
	v_mfma_f32_16x16x32_bf16 v[32:35], v[186:189], v[220:223], v[32:35]
	v_mfma_f32_16x16x32_bf16 v[8:11], v[178:181], v[228:231], v[8:11]
	v_mfma_f32_16x16x32_bf16 v[16:19], v[186:189], v[228:231], v[16:19]
	v_mfma_f32_16x16x32_bf16 v[56:59], v[182:185], v[198:201], v[56:59]
	v_mfma_f32_16x16x32_bf16 v[64:67], v[190:193], v[198:201], v[64:67]
	v_mfma_f32_16x16x32_bf16 v[40:43], v[182:185], v[216:219], v[40:43]
	v_mfma_f32_16x16x32_bf16 v[48:51], v[190:193], v[216:219], v[48:51]
	v_mfma_f32_16x16x32_bf16 v[24:27], v[182:185], v[224:227], v[24:27]
	v_mfma_f32_16x16x32_bf16 v[32:35], v[190:193], v[224:227], v[32:35]
	v_mfma_f32_16x16x32_bf16 v[8:11], v[182:185], v[232:235], v[8:11]
	v_mfma_f32_16x16x32_bf16 v[16:19], v[190:193], v[232:235], v[16:19]
	s_setprio 0
	s_barrier
	s_add_i32 s80, s80, 2
	s_cmp_gt_u32 s80, 61
	s_cbranch_scc0 .LBB0_1460
	s_and_b64 vcc, exec, s[14:15]
	s_cbranch_vccz .LBB0_1463
	s_barrier
